# thin sample-row GEMM task loops of the in- and out-projection: blocks of 4 / 2 tasks issue all operand loads before the MFMA chains (on top of the static-priority version)
# baseline (speedup 1.0000x reference)
; #define MFMA(X, Y, C) __builtin_amdgcn_mfma_f32_16x16x32_bf16((X), (Y), (C), 0, 0, 0)
; template <int K, int MODE  >
; __device__ __forceinline__ void thin_gemm(LAS unsigned char* lds, const bf16_t* A, const bf16_t* Bt, int N, void* out, int ldc, bf16_t* xb, u64* rss) {
;     ...
;         for (int i = 0; i < nr; ++i) {
;             const int t = base + i, ct = t >> 3, rt = t & 7;
;             const bf16_t* ap = A + (size_t)(rt * 16 + fr) * K + wid * KW + 8 * fq;
;             const bf16_t* bp = Bt + (size_t)(ct * 16 + fr) * K + wid * KW + 8 * fq;
;             bf16x8 a[STEPS], b[STEPS];
; #pragma unroll
;             for (int s = 0; s < STEPS; ++s) { a[s] = *(const bf16x8*)(ap + 32 * s); b[s] = *(const bf16x8*)(bp + 32 * s); }
;             f32x4 acc = {0.f, 0.f, 0.f, 0.f};
; #pragma unroll
;             for (int s = 0; s < STEPS; ++s) acc = MFMA(b[s], a[s], acc);
;             red[(i * 8 + wid) * 64 + lane] = acc;
.LBB0_291:
	s_cmp_lt_u32 s1, 0x4000
	s_cbranch_scc1 .Lthin_s4_single
	s_waitcnt lgkmcnt(0)
	s_add_i32 s37, s30, 0
	s_and_b32 s37, s37, 0x70
	s_add_i32 s40, s36, 0
	v_and_or_b32 v0, s40, -16, v7
	s_nop 2
	v_or_b32_e32 v118, s37, v7
	v_mad_i64_i32 v[116:117], s[40:41], v0, s43, v[4:5]
	v_mul_u32_u24_e32 v0, 0x600, v118
	v_lshlrev_b32_e32 v0, 1, v0
	v_lshl_add_u64 v[42:43], v[2:3], 0, v[0:1]
	global_load_dwordx4 v[14:17], v[116:117], off
	global_load_dwordx4 v[18:21], v[116:117], off offset:64
	global_load_dwordx4 v[22:25], v[116:117], off offset:128
	global_load_dwordx4 v[26:29], v[116:117], off offset:192
	global_load_dwordx4 v[30:33], v[116:117], off offset:256
	global_load_dwordx4 v[34:37], v[116:117], off offset:320
	global_load_dwordx4 v[38:41], v[42:43], off
	global_load_dwordx4 v[44:47], v[42:43], off offset:64
	global_load_dwordx4 v[48:51], v[42:43], off offset:128
	global_load_dwordx4 v[52:55], v[42:43], off offset:192
	global_load_dwordx4 v[56:59], v[42:43], off offset:256
	global_load_dwordx4 v[60:63], v[42:43], off offset:320
	s_add_i32 s37, s30, 16
	s_and_b32 s37, s37, 0x70
	s_add_i32 s40, s36, 2
	v_and_or_b32 v0, s40, -16, v7
	s_nop 2
	v_or_b32_e32 v118, s37, v7
	v_mad_i64_i32 v[112:113], s[40:41], v0, s43, v[4:5]
	v_mul_u32_u24_e32 v0, 0x600, v118
	v_lshlrev_b32_e32 v0, 1, v0
	v_lshl_add_u64 v[114:115], v[2:3], 0, v[0:1]
	global_load_dwordx4 v[64:67], v[112:113], off
	global_load_dwordx4 v[68:71], v[112:113], off offset:64
	global_load_dwordx4 v[72:75], v[112:113], off offset:128
	global_load_dwordx4 v[76:79], v[112:113], off offset:192
	global_load_dwordx4 v[80:83], v[112:113], off offset:256
	global_load_dwordx4 v[84:87], v[112:113], off offset:320
	global_load_dwordx4 v[88:91], v[114:115], off
	global_load_dwordx4 v[92:95], v[114:115], off offset:64
	global_load_dwordx4 v[96:99], v[114:115], off offset:128
	global_load_dwordx4 v[100:103], v[114:115], off offset:192
	global_load_dwordx4 v[104:107], v[114:115], off offset:256
	global_load_dwordx4 v[108:111], v[114:115], off offset:320
	s_waitcnt vmcnt(17)
	v_mfma_f32_16x16x32_bf16 v[14:17], v[14:17], v[38:41], 0
	s_waitcnt vmcnt(16)
	v_mfma_f32_16x16x32_bf16 v[14:17], v[18:21], v[44:47], v[14:17]
	s_waitcnt vmcnt(15)
	v_mfma_f32_16x16x32_bf16 v[14:17], v[22:25], v[48:51], v[14:17]
	s_waitcnt vmcnt(14)
	v_mfma_f32_16x16x32_bf16 v[14:17], v[26:29], v[52:55], v[14:17]
	s_waitcnt vmcnt(13)
	v_mfma_f32_16x16x32_bf16 v[14:17], v[30:33], v[56:59], v[14:17]
	s_waitcnt vmcnt(12)
	v_mfma_f32_16x16x32_bf16 v[14:17], v[34:37], v[60:63], v[14:17]
	s_nop 7
	ds_write_b128 v13, v[14:17]
	v_add_u32_e32 v13, 0x2000, v13
	s_waitcnt vmcnt(5)
	v_mfma_f32_16x16x32_bf16 v[64:67], v[64:67], v[88:91], 0
	s_waitcnt vmcnt(4)
	v_mfma_f32_16x16x32_bf16 v[64:67], v[68:71], v[92:95], v[64:67]
	s_waitcnt vmcnt(3)
	v_mfma_f32_16x16x32_bf16 v[64:67], v[72:75], v[96:99], v[64:67]
	s_waitcnt vmcnt(2)
	v_mfma_f32_16x16x32_bf16 v[64:67], v[76:79], v[100:103], v[64:67]
	s_waitcnt vmcnt(1)
	v_mfma_f32_16x16x32_bf16 v[64:67], v[80:83], v[104:107], v[64:67]
	s_waitcnt vmcnt(0)
	v_mfma_f32_16x16x32_bf16 v[64:67], v[84:87], v[108:111], v[64:67]
	s_nop 7
	ds_write_b128 v13, v[64:67]
	v_add_u32_e32 v13, 0x2000, v13
	s_addk_i32 s1, 0xc000
	s_add_i32 s36, s36, 4
	s_add_i32 s30, s30, 32
	s_cmp_eq_u32 s1, 0
	s_cbranch_scc0 .LBB0_291
	s_branch .LBB0_292

; #define MFMA(X, Y, C) __builtin_amdgcn_mfma_f32_16x16x32_bf16((X), (Y), (C), 0, 0, 0)
; template <int K, int MODE  >
; __device__ __forceinline__ void thin_gemm(LAS unsigned char* lds, const bf16_t* A, const bf16_t* Bt, int N, void* out, int ldc, bf16_t* xb, u64* rss) {
;     ...
;         for (int i = 0; i < nr; ++i) {
;             const int t = base + i, ct = t >> 3, rt = t & 7;
;             const bf16_t* ap = A + (size_t)(rt * 16 + fr) * K + wid * KW + 8 * fq;
;             const bf16_t* bp = Bt + (size_t)(ct * 16 + fr) * K + wid * KW + 8 * fq;
;             bf16x8 a[STEPS], b[STEPS];
; #pragma unroll
;             for (int s = 0; s < STEPS; ++s) { a[s] = *(const bf16x8*)(ap + 32 * s); b[s] = *(const bf16x8*)(bp + 32 * s); }
;             f32x4 acc = {0.f, 0.f, 0.f, 0.f};
; #pragma unroll
;             for (int s = 0; s < STEPS; ++s) acc = MFMA(b[s], a[s], acc);
;             red[(i * 8 + wid) * 64 + lane] = acc;
.LBB0_522:
	s_cmp_lt_u32 s23, 0x8000
	s_cbranch_scc1 .Lthin_s0_single
	s_waitcnt lgkmcnt(0)
	s_add_i32 s37, s36, 0
	v_and_or_b32 v8, s37, -16, v11
	s_add_i32 s37, s30, 0
	s_and_b32 s37, s37, 0x70
	v_ashrrev_i32_e32 v9, 31, v8
	v_or_b32_e32 v0, s37, v11
	v_lshlrev_b64 v[8:9], 11, v[8:9]
	v_lshlrev_b32_e32 v0, 11, v0
	v_lshl_add_u64 v[8:9], v[4:5], 0, v[8:9]
	v_lshl_add_u64 v[36:37], v[2:3], 0, v[0:1]
	global_load_dwordx4 v[16:19], v[8:9], off
	global_load_dwordx4 v[24:27], v[8:9], off offset:64
	global_load_dwordx4 v[32:35], v[8:9], off offset:128
	global_load_dwordx4 v[40:43], v[8:9], off offset:192
	global_load_dwordx4 v[20:23], v[36:37], off
	global_load_dwordx4 v[28:31], v[36:37], off offset:64
	global_load_dwordx4 v[44:47], v[36:37], off offset:128
	global_load_dwordx4 v[48:51], v[36:37], off offset:192
	s_add_i32 s37, s36, 2
	v_and_or_b32 v148, s37, -16, v11
	s_add_i32 s37, s30, 16
	s_and_b32 s37, s37, 0x70
	v_ashrrev_i32_e32 v149, 31, v148
	v_or_b32_e32 v0, s37, v11
	v_lshlrev_b64 v[148:149], 11, v[148:149]
	v_lshlrev_b32_e32 v0, 11, v0
	v_lshl_add_u64 v[148:149], v[4:5], 0, v[148:149]
	v_lshl_add_u64 v[150:151], v[2:3], 0, v[0:1]
	global_load_dwordx4 v[52:55], v[148:149], off
	global_load_dwordx4 v[56:59], v[148:149], off offset:64
	global_load_dwordx4 v[60:63], v[148:149], off offset:128
	global_load_dwordx4 v[64:67], v[148:149], off offset:192
	global_load_dwordx4 v[68:71], v[150:151], off
	global_load_dwordx4 v[72:75], v[150:151], off offset:64
	global_load_dwordx4 v[76:79], v[150:151], off offset:128
	global_load_dwordx4 v[80:83], v[150:151], off offset:192
	s_add_i32 s37, s36, 4
	v_and_or_b32 v152, s37, -16, v11
	s_add_i32 s37, s30, 32
	s_and_b32 s37, s37, 0x70
	v_ashrrev_i32_e32 v153, 31, v152
	v_or_b32_e32 v0, s37, v11
	v_lshlrev_b64 v[152:153], 11, v[152:153]
	v_lshlrev_b32_e32 v0, 11, v0
	v_lshl_add_u64 v[152:153], v[4:5], 0, v[152:153]
	v_lshl_add_u64 v[154:155], v[2:3], 0, v[0:1]
	global_load_dwordx4 v[84:87], v[152:153], off
	global_load_dwordx4 v[88:91], v[152:153], off offset:64
	global_load_dwordx4 v[92:95], v[152:153], off offset:128
	global_load_dwordx4 v[96:99], v[152:153], off offset:192
	global_load_dwordx4 v[100:103], v[154:155], off
	global_load_dwordx4 v[104:107], v[154:155], off offset:64
	global_load_dwordx4 v[108:111], v[154:155], off offset:128
	global_load_dwordx4 v[112:115], v[154:155], off offset:192
	s_add_i32 s37, s36, 6
	v_and_or_b32 v156, s37, -16, v11
	s_add_i32 s37, s30, 48
	s_and_b32 s37, s37, 0x70
	v_ashrrev_i32_e32 v157, 31, v156
	v_or_b32_e32 v0, s37, v11
	v_lshlrev_b64 v[156:157], 11, v[156:157]
	v_lshlrev_b32_e32 v0, 11, v0
	v_lshl_add_u64 v[156:157], v[4:5], 0, v[156:157]
	v_lshl_add_u64 v[158:159], v[2:3], 0, v[0:1]
	global_load_dwordx4 v[116:119], v[156:157], off
	global_load_dwordx4 v[120:123], v[156:157], off offset:64
	global_load_dwordx4 v[124:127], v[156:157], off offset:128
	global_load_dwordx4 v[128:131], v[156:157], off offset:192
	global_load_dwordx4 v[132:135], v[158:159], off
	global_load_dwordx4 v[136:139], v[158:159], off offset:64
	global_load_dwordx4 v[140:143], v[158:159], off offset:128
	global_load_dwordx4 v[144:147], v[158:159], off offset:192
	s_waitcnt vmcnt(27)
	v_mfma_f32_16x16x32_bf16 v[16:19], v[16:19], v[20:23], 0
	s_waitcnt vmcnt(26)
	v_mfma_f32_16x16x32_bf16 v[16:19], v[24:27], v[28:31], v[16:19]
	s_waitcnt vmcnt(25)
	v_mfma_f32_16x16x32_bf16 v[16:19], v[32:35], v[44:47], v[16:19]
	s_waitcnt vmcnt(24)
	v_mfma_f32_16x16x32_bf16 v[16:19], v[40:43], v[48:51], v[16:19]
	s_nop 7
	ds_write_b128 v6, v[16:19]
	v_add_u32_e32 v6, 0x2000, v6
	s_waitcnt vmcnt(19)
	v_mfma_f32_16x16x32_bf16 v[52:55], v[52:55], v[68:71], 0
	s_waitcnt vmcnt(18)
	v_mfma_f32_16x16x32_bf16 v[52:55], v[56:59], v[72:75], v[52:55]
	s_waitcnt vmcnt(17)
	v_mfma_f32_16x16x32_bf16 v[52:55], v[60:63], v[76:79], v[52:55]
	s_waitcnt vmcnt(16)
	v_mfma_f32_16x16x32_bf16 v[52:55], v[64:67], v[80:83], v[52:55]
	s_nop 7
	ds_write_b128 v6, v[52:55]
	v_add_u32_e32 v6, 0x2000, v6
	s_waitcnt vmcnt(11)
	v_mfma_f32_16x16x32_bf16 v[84:87], v[84:87], v[100:103], 0
	s_waitcnt vmcnt(10)
	v_mfma_f32_16x16x32_bf16 v[84:87], v[88:91], v[104:107], v[84:87]
	s_waitcnt vmcnt(9)
	v_mfma_f32_16x16x32_bf16 v[84:87], v[92:95], v[108:111], v[84:87]
	s_waitcnt vmcnt(8)
	v_mfma_f32_16x16x32_bf16 v[84:87], v[96:99], v[112:115], v[84:87]
	s_nop 7
	ds_write_b128 v6, v[84:87]
	v_add_u32_e32 v6, 0x2000, v6
	s_waitcnt vmcnt(3)
	v_mfma_f32_16x16x32_bf16 v[116:119], v[116:119], v[132:135], 0
	s_waitcnt vmcnt(2)
	v_mfma_f32_16x16x32_bf16 v[116:119], v[120:123], v[136:139], v[116:119]
	s_waitcnt vmcnt(1)
	v_mfma_f32_16x16x32_bf16 v[116:119], v[124:127], v[140:143], v[116:119]
	s_waitcnt vmcnt(0)
	v_mfma_f32_16x16x32_bf16 v[116:119], v[128:131], v[144:147], v[116:119]
	s_nop 7
	ds_write_b128 v6, v[116:119]
	v_add_u32_e32 v6, 0x2000, v6
	s_addk_i32 s23, 0x8000
	s_add_i32 s36, s36, 8
	s_add_i32 s30, s30, 64
	s_cmp_eq_u32 s23, 0
	s_cbranch_scc0 .LBB0_522
	s_branch .LBB0_523
